# v64 + prep: q/k/q-lora/kv-lora RMSNorm gain vectors staged in LDS (ds_read per row)
# speedup vs baseline: 1.1341x; 1.0026x over previous
.LBB0_565:
	s_andn2_b64 vcc, exec, s[36:37]
	s_cbranch_vccnz .LBB0_613
	s_waitcnt vmcnt(0)
	v_mov_b32_e32 v4, v168
	v_mov_b32_e32 v0, v168
	v_readlane_b32 s0, v254, 7
	v_ashrrev_i32_e32 v0, 6, v0
	s_movk_i32 s2, 0x3800
	v_add_u32_e32 v0, s0, v0
	v_readlane_b32 s0, v254, 46
	v_cmp_gt_i32_e32 vcc, s2, v0
	v_readlane_b32 s1, v254, 47
	s_and_saveexec_b64 s[60:61], vcc
	s_cbranch_execz .LBB0_612
	v_readlane_b32 s0, v254, 61
	v_readlane_b32 s80, v250, 17
	v_and_b32_e32 v1, 63, v4
	v_readlane_b32 s1, v254, 62
	s_mul_i32 s20, s0, 0x4800
	v_readlane_b32 s90, v250, 27
	v_lshlrev_b32_e32 v72, 3, v1
	s_mul_i32 s2, s0, 0x180
	s_mul_hi_i32 s3, s0, 0x4800
	v_readlane_b32 s91, v250, 28
	s_add_u32 s52, s90, s20
	v_and_b32_e32 v74, 56, v72
	v_and_b32_e32 v5, 0xf8, v72
	v_readlane_b32 s1, v254, 63
	s_addc_u32 s53, s91, s3
	v_bfe_u32 v3, v4, 3, 3
	s_waitcnt lgkmcnt(0)
	v_or_b32_e32 v6, s1, v74
	v_and_b32_e32 v12, 2, v4
	v_and_b32_e32 v13, 1, v4
	v_add_u32_e32 v8, s2, v72
	v_lshl_or_b32 v10, s0, 8, v5
	v_readlane_b32 s0, v250, 1
	v_cmp_eq_u32_e64 s[48:49], 0, v12
	v_cmp_eq_u32_e64 s[50:51], 0, v13
	v_lshlrev_b32_e32 v12, 8, v3
	v_mov_b32_e32 v13, v2
	v_readlane_b32 s2, v250, 3
	v_readlane_b32 s3, v250, 4
	v_readlane_b32 s4, v250, 5
	v_readlane_b32 s5, v250, 6
	v_lshlrev_b32_e32 v16, 2, v74
	v_mov_b32_e32 v17, v2
	v_lshl_add_u64 v[14:15], s[4:5], 0, v[12:13]
	v_readlane_b32 s2, v252, 59
	v_lshl_add_u64 v[78:79], v[14:15], 0, v[16:17]
	v_lshlrev_b32_e32 v14, 1, v74
	v_mov_b32_e32 v15, v2
	v_readlane_b32 s3, v252, 60
	v_readlane_b32 s6, v250, 7
	v_readlane_b32 s7, v250, 8
	v_lshl_add_u64 v[86:87], s[2:3], 0, v[14:15]
	v_readlane_b32 s2, v253, 44
	v_lshl_add_u64 v[12:13], s[6:7], 0, v[12:13]
	v_lshlrev_b32_e32 v14, 4, v1
	v_readlane_b32 s3, v253, 45
	v_readlane_b32 s8, v250, 9
	v_readlane_b32 s9, v250, 10
	v_readlane_b32 s10, v250, 11
	v_readlane_b32 s11, v250, 12
	v_readlane_b32 s12, v250, 13
	v_readlane_b32 s13, v250, 14
	v_readlane_b32 s14, v250, 15
	v_readlane_b32 s15, v250, 16
	v_lshl_add_u64 v[80:81], v[12:13], 0, v[16:17]
	v_lshlrev_b32_e32 v12, 5, v1
	v_mov_b32_e32 v13, v2
	v_lshl_add_u64 v[88:89], s[2:3], 0, v[14:15]
	v_readlane_b32 s2, v252, 49
	v_ashrrev_i32_e32 v7, 31, v6
	v_lshl_add_u64 v[82:83], s[8:9], 0, v[12:13]
	v_lshl_add_u64 v[84:85], s[10:11], 0, v[12:13]
	v_readlane_b32 s4, v254, 30
	v_readlane_b32 s3, v252, 50
	v_readlane_b32 s81, v250, 18
	v_bfe_u32 v73, v4, 3, 1
	v_readlane_b32 s18, v254, 44
	v_readlane_b32 s19, v254, 45
	v_lshl_add_u64 v[90:91], s[2:3], 0, v[14:15]
	v_lshlrev_b64 v[6:7], 2, v[6:7]
	v_readlane_b32 s2, v253, 24
	v_lshl_add_u64 v[92:93], s[18:19], 0, v[6:7]
	v_lshl_add_u64 v[94:95], s[80:81], 0, v[6:7]
	v_lshlrev_b32_e32 v6, 8, v73
	v_mov_b32_e32 v7, v2
	v_readlane_b32 s3, v253, 25
	v_lshl_add_u64 v[104:105], s[52:53], 0, v[12:13]
	s_mov_b64 s[20:21], 0x1800
	v_lshl_add_u64 v[18:19], s[2:3], 0, v[6:7]
	v_readlane_b32 s2, v253, 26
	v_readlane_b32 s3, v253, 27
	v_lshl_add_u64 v[106:107], v[104:105], 0, s[20:21]
	s_mov_b64 s[20:21], 0x3800
	v_lshl_add_u64 v[6:7], s[2:3], 0, v[6:7]
	s_mov_b64 s[2:3], 0x3000
	v_lshl_add_u64 v[108:109], v[104:105], 0, s[2:3]
	s_mov_b64 s[2:3], 0x2000
	v_lshl_add_u64 v[110:111], v[104:105], 0, s[2:3]
	s_mov_b64 s[2:3], 0x1000
	v_lshl_add_u64 v[114:115], v[104:105], 0, s[2:3]
	s_mov_b64 s[2:3], 0x2800
	v_lshl_add_u64 v[116:117], v[104:105], 0, s[2:3]
	s_mov_b64 s[2:3], 0x4000
	v_lshl_add_u64 v[118:119], v[104:105], 0, s[2:3]
	s_movk_i32 s2, 0x300
	v_lshl_add_u64 v[98:99], v[6:7], 0, v[16:17]
	v_lshl_add_u64 v[112:113], v[104:105], 0, s[20:21]
	v_mad_i64_i32 v[6:7], s[20:21], v0, s2, v[14:15]
	s_mov_b64 s[20:21], 0x6c50000
	s_movk_i32 s2, 0x1740
	v_and_b32_e32 v20, 15, v4
	v_and_b32_e32 v22, 3, v4
	v_lshl_add_u64 v[120:121], v[6:7], 0, s[20:21]
	v_mad_i64_i32 v[6:7], s[20:21], v0, s2, 0
	v_and_b32_e32 v4, 31, v4
	v_lshl_or_b32 v6, v22, 4, v6
	s_mov_b64 s[20:21], 0x1390b00
	v_lshlrev_b32_e32 v4, 4, v4
	v_mov_b32_e32 v5, v2
	v_cmp_gt_u32_e64 s[42:43], 48, v1
	v_lshl_add_u64 v[124:125], v[6:7], 0, s[20:21]
	v_mad_i64_i32 v[4:5], s[20:21], v0, s2, v[4:5]
	v_cndmask_b32_e64 v21, 0, v72, s[42:43]
	s_mov_b64 s[20:21], 0x1390900
	v_lshl_add_u64 v[126:127], v[4:5], 0, s[20:21]
	v_lshlrev_b32_e32 v4, 1, v21
	v_mov_b32_e32 v5, v2
	v_mad_i64_i32 v[4:5], s[20:21], v0, s2, v[4:5]
	v_cmp_gt_u32_e64 s[36:37], 16, v1
	v_cmp_gt_u32_e64 s[38:39], 32, v1
	v_cmp_gt_u32_e64 s[40:41], 4, v1
	v_readlane_b32 s1, v250, 2
	v_ashrrev_i32_e32 v1, 31, v0
	s_mov_b64 s[20:21], 0x1390600
	v_readlane_b32 s82, v250, 19
	v_readlane_b32 s83, v250, 20
	v_readlane_b32 s84, v250, 21
	v_readlane_b32 s85, v250, 22
	v_and_b32_e32 v23, 8, v72
	v_ashrrev_i32_e32 v9, 31, v8
	v_ashrrev_i32_e32 v11, 31, v10
	v_readlane_b32 s0, v254, 46
	v_lshlrev_b64 v[122:123], 10, v[0:1]
	v_lshl_add_u64 v[128:129], v[4:5], 0, s[20:21]
	v_lshlrev_b32_e32 v4, 4, v20
	v_mov_b32_e32 v5, v2
	v_cmp_gt_u32_e64 s[44:45], 32, v74
	v_lshlrev_b32_e32 v76, 9, v74
	v_mov_b32_e32 v77, v2
	v_cmp_lt_u32_e64 s[46:47], 1, v22
	v_readlane_b32 s1, v254, 47
	v_readlane_b32 s5, v254, 31
	v_readlane_b32 s6, v254, 32
	v_readlane_b32 s7, v254, 33
	v_readlane_b32 s8, v254, 34
	v_readlane_b32 s9, v254, 35
	v_readlane_b32 s10, v254, 36
	v_readlane_b32 s11, v254, 37
	v_readlane_b32 s12, v254, 38
	v_readlane_b32 s13, v254, 39
	v_readlane_b32 s14, v254, 40
	v_readlane_b32 s15, v254, 41
	v_readlane_b32 s16, v254, 42
	v_readlane_b32 s17, v254, 43
	v_lshl_add_u64 v[96:97], v[18:19], 0, v[16:17]
	v_lshl_add_u64 v[100:101], v[8:9], 2, s[82:83]
	v_lshl_add_u64 v[102:103], v[10:11], 2, s[84:85]
	v_or_b32_e32 v122, v122, v14
	v_mad_i64_i32 v[130:131], s[20:21], v0, s2, v[4:5]
	v_mad_i64_i32 v[132:133], s[20:21], v0, s2, v[14:15]
	s_mov_b64 s[62:63], 0
	v_lshlrev_b32_e32 v75, 2, v23
	v_readlane_b32 s86, v250, 23
	v_readlane_b32 s87, v250, 24
	v_readlane_b32 s88, v250, 25
	v_readlane_b32 s89, v250, 26
	v_readlane_b32 s92, v250, 29
	v_readlane_b32 s93, v250, 30
	v_readlane_b32 s94, v250, 31
	v_readlane_b32 s95, v250, 32
	v_and_b32_e32 v162, 63, v168
	v_lshlrev_b32_e32 v162, 5, v162
	v_lshlrev_b32_e32 v163, 4, v168
	v_add_u32_e32 v164, 0x1000, v163
	v_add_u32_e32 v165, 0x2000, v163
	v_add_u32_e32 v166, 0x3000, v163
	v_add_u32_e32 v167, 0x4000, v163
	v_min_u32_e32 v167, 0x47f0, v167
	global_load_dwordx4 v[202:205], v163, s[52:53]
	global_load_dwordx4 v[206:209], v164, s[52:53]
	global_load_dwordx4 v[210:213], v165, s[52:53]
	global_load_dwordx4 v[214:217], v166, s[52:53]
	global_load_dwordx4 v[218:221], v167, s[52:53]
	v_and_b32_e32 v188, 7, v168
	v_lshlrev_b32_e32 v188, 5, v188
	v_and_b32_e32 v189, 31, v168
	v_lshlrev_b32_e32 v189, 5, v189
	v_readlane_b32 s0, v254, 61
	v_min_u32_e32 v190, 0xf0, v163
	v_min_u32_e32 v191, 0x5f0, v163
	v_min_u32_e32 v222, 0x3f0, v163
	s_lshl_b32 s1, s0, 8
	v_add_u32_e32 v223, s1, v190
	s_mul_i32 s1, s0, 0x600
	v_add_u32_e32 v224, s1, v191
	s_lshl_b32 s1, s0, 10
	v_add_u32_e32 v225, s1, v222
	global_load_dwordx4 v[226:229], v223, s[18:19]
	global_load_dwordx4 v[230:233], v223, s[80:81]
	global_load_dwordx4 v[234:237], v224, s[82:83]
	global_load_dwordx4 v[238:241], v225, s[84:85]
	s_waitcnt vmcnt(0)
	ds_write_b128 v163, v[202:205]
	ds_write_b128 v164, v[206:209]
	ds_write_b128 v165, v[210:213]
	ds_write_b128 v166, v[214:217]
	ds_write_b128 v167, v[218:221]
	ds_write_b128 v190, v[226:229] offset:18432
	ds_write_b128 v190, v[230:233] offset:18688
	ds_write_b128 v191, v[234:237] offset:18944
	ds_write_b128 v222, v[238:241] offset:20480
	s_waitcnt lgkmcnt(0)
	s_barrier
	v_readlane_b32 s0, v254, 46
	v_readlane_b32 s1, v254, 47
	s_branch .LBB0_570

.LBB0_591:
	s_or_b64 exec, exec, s[56:57]
	ds_read_b128 v[66:69], v188 offset:18432
	ds_read_b128 v[134:137], v188 offset:18448
	s_waitcnt vmcnt(3)
	v_lshlrev_b32_e32 v70, 16, v60
	v_and_b32_e32 v71, 0xffff0000, v60
	v_lshlrev_b32_e32 v60, 16, v61
	v_and_b32_e32 v61, 0xffff0000, v61
	v_pk_mul_f32 v[144:145], v[70:71], v[70:71]
	v_pk_mul_f32 v[146:147], v[60:61], v[60:61]
	v_add_f32_e32 v141, v144, v145
	v_lshlrev_b32_e32 v138, 16, v62
	v_and_b32_e32 v139, 0xffff0000, v62
	v_add_f32_e32 v141, v146, v141
	v_pk_mul_f32 v[148:149], v[138:139], v[138:139]
	v_add_f32_e32 v141, v147, v141
	v_and_b32_e32 v64, 0xffff0000, v63
	v_lshlrev_b32_e32 v65, 16, v63
	v_add_f32_e32 v141, v148, v141
	v_cmp_lt_i32_e32 vcc, v185, v182
	v_pk_mul_f32 v[62:63], v[64:65], v[64:65]
	v_add_f32_e32 v141, v149, v141
	v_cndmask_b32_e32 v140, v179, v185, vcc
	v_add_f32_e32 v63, v63, v141
	v_lshlrev_b32_e32 v140, 2, v140
	v_add_f32_e32 v62, v62, v63
	ds_bpermute_b32 v63, v140, v62
	v_cmp_lt_i32_e32 vcc, v186, v182
	s_waitcnt lgkmcnt(0)
	v_add_f32_e32 v62, v62, v63
	v_cndmask_b32_e32 v141, v179, v186, vcc
	v_lshlrev_b32_e32 v141, 2, v141
	ds_bpermute_b32 v63, v141, v62
	v_cmp_lt_i32_e32 vcc, v187, v182
	s_waitcnt lgkmcnt(0)
	v_add_f32_e32 v62, v62, v63
	v_cndmask_b32_e32 v142, v179, v187, vcc
	v_lshlrev_b32_e32 v142, 2, v142
	ds_bpermute_b32 v63, v142, v62
	s_waitcnt lgkmcnt(0)
	v_add_f32_e32 v62, v62, v63
	v_fmamk_f32 v62, v62, 0x3c800000, v174
	v_rsq_f32_e32 v62, v62
	s_nop 0
	v_pk_mul_f32 v[70:71], v[62:63], v[70:71] op_sel_hi:[0,1]
	v_pk_mul_f32 v[60:61], v[62:63], v[60:61] op_sel_hi:[0,1]
	v_pk_mul_f32 v[138:139], v[62:63], v[138:139] op_sel_hi:[0,1]
	v_pk_mul_f32 v[144:145], v[62:63], v[64:65] op_sel_hi:[0,1]
	s_waitcnt vmcnt(0) lgkmcnt(0)
	v_pk_mul_f32 v[66:67], v[66:67], v[70:71]
	v_pk_mul_f32 v[64:65], v[68:69], v[60:61]
	s_nop 0
	v_pk_mul_f32 v[62:63], v[134:135], v[138:139]
	v_pk_mul_f32 v[60:61], v[144:145], v[136:137] op_sel:[1,0] op_sel_hi:[0,1]
	ds_bpermute_b32 v70, v141, v66
	ds_bpermute_b32 v71, v141, v67
	ds_bpermute_b32 v136, v141, v64
	ds_bpermute_b32 v137, v141, v65
	ds_bpermute_b32 v68, v141, v62
	ds_bpermute_b32 v69, v141, v63
	ds_bpermute_b32 v134, v141, v60
	ds_bpermute_b32 v135, v141, v61
	v_lshrrev_b32_e32 v144, 6, v143
	v_and_b32_e32 v145, 63, v0
	v_cndmask_b32_e64 v138, v145, v144, s[44:45]
	s_and_saveexec_b64 s[56:57], s[54:55]
	s_cbranch_execz .LBB0_593
	v_readlane_b32 s80, v254, 48
	v_lshl_or_b32 v158, v138, 6, v75
	v_mov_b32_e32 v159, v2
	v_readlane_b32 s84, v254, 52
	v_readlane_b32 s85, v254, 53
	s_mov_b64 s[2:3], 0x1000
	v_readlane_b32 s81, v254, 49
	v_lshl_add_u64 v[150:151], s[84:85], 0, v[158:159]
	v_add_co_u32_e32 v146, vcc, 0x1000, v150
	v_readlane_b32 s82, v254, 50
	s_nop 0
	v_addc_co_u32_e32 v147, vcc, 0, v151, vcc
	global_load_dwordx4 v[146:149], v[146:147], off
	v_lshl_add_u64 v[150:151], v[150:151], 0, s[2:3]
	global_load_dwordx4 v[150:153], v[150:151], off offset:16
	s_nop 0
	global_load_dwordx4 v[154:157], v158, s[84:85]
	s_nop 0
	global_load_dwordx4 v[158:161], v158, s[84:85] offset:16
	v_readlane_b32 s83, v254, 51
	v_readlane_b32 s86, v254, 54
	v_readlane_b32 s87, v254, 55
	s_waitcnt vmcnt(2) lgkmcnt(2)
	v_pk_mul_f32 v[68:69], v[150:151], v[68:69]
	v_pk_mul_f32 v[70:71], v[146:147], v[70:71]
	v_pk_mul_f32 v[136:137], v[148:149], v[136:137]
	s_waitcnt lgkmcnt(0)
	v_pk_mul_f32 v[134:135], v[152:153], v[134:135]
	v_cndmask_b32_e64 v137, v137, -v137, s[48:49]
	v_cndmask_b32_e64 v136, v136, -v136, s[48:49]
	v_cndmask_b32_e64 v71, v71, -v71, s[48:49]
	v_cndmask_b32_e64 v70, v70, -v70, s[48:49]
	v_cndmask_b32_e64 v135, v135, -v135, s[48:49]
	v_cndmask_b32_e64 v134, v134, -v134, s[48:49]
	v_cndmask_b32_e64 v69, v69, -v69, s[48:49]
	v_cndmask_b32_e64 v68, v68, -v68, s[48:49]
	s_waitcnt vmcnt(1)
	v_pk_fma_f32 v[64:65], v[64:65], v[156:157], v[136:137]
	s_waitcnt vmcnt(0)
	v_pk_fma_f32 v[60:61], v[60:61], v[160:161], v[134:135]
	v_pk_fma_f32 v[66:67], v[66:67], v[154:155], v[70:71]
	v_pk_fma_f32 v[62:63], v[62:63], v[158:159], v[68:69]
.LBB0_593:
	s_or_b64 exec, exec, s[56:57]
	v_readlane_b32 s80, v254, 48
	s_mov_b32 s2, 0x3e38aa3b
	v_readlane_b32 s84, v254, 52
	v_readlane_b32 s85, v254, 53
	v_pk_mul_f32 v[66:67], v[66:67], s[2:3] op_sel_hi:[1,0]
	v_pk_mul_f32 v[64:65], v[64:65], s[2:3] op_sel_hi:[1,0]
	v_pk_mul_f32 v[62:63], v[62:63], s[2:3] op_sel_hi:[1,0]
	s_waitcnt lgkmcnt(2)
	v_pk_mul_f32 v[68:69], v[60:61], s[2:3] op_sel_hi:[1,0]
	s_waitcnt lgkmcnt(0)
	v_lshl_add_u64 v[134:135], s[84:85], 0, v[122:123]
	s_mov_b32 s2, 0x5950000
	v_cvt_pk_bf16_f32 v61, v64, v65
	v_add_co_u32_e32 v64, vcc, s2, v134
	v_cvt_pk_bf16_f32 v60, v66, v67
	v_cvt_pk_bf16_f32 v62, v62, v63
	v_cvt_pk_bf16_f32 v63, v68, v69
	v_addc_co_u32_e32 v65, vcc, 0, v135, vcc
	global_store_dwordx4 v[64:65], v[60:63], off
	s_nop 1
	ds_read_b128 v[60:63], v188 offset:18688
	s_nop 0
	ds_read_b128 v[64:67], v188 offset:18704
	v_lshlrev_b32_e32 v70, 16, v56
	v_and_b32_e32 v71, 0xffff0000, v56
	v_lshlrev_b32_e32 v56, 16, v57
	v_and_b32_e32 v57, 0xffff0000, v57
	v_pk_mul_f32 v[146:147], v[70:71], v[70:71]
	v_pk_mul_f32 v[148:149], v[56:57], v[56:57]
	v_add_f32_e32 v139, v146, v147
	v_lshlrev_b32_e32 v136, 16, v58
	v_and_b32_e32 v137, 0xffff0000, v58
	v_add_f32_e32 v139, v148, v139
	v_pk_mul_f32 v[150:151], v[136:137], v[136:137]
	v_add_f32_e32 v139, v149, v139
	v_and_b32_e32 v68, 0xffff0000, v59
	v_lshlrev_b32_e32 v69, 16, v59
	v_add_f32_e32 v139, v150, v139
	v_pk_mul_f32 v[58:59], v[68:69], v[68:69]
	v_add_f32_e32 v139, v151, v139
	v_add_f32_e32 v59, v59, v139
	v_add_f32_e32 v58, v58, v59
	ds_bpermute_b32 v59, v140, v58
	v_readlane_b32 s81, v254, 49
	v_readlane_b32 s82, v254, 50
	v_readlane_b32 s83, v254, 51
	v_readlane_b32 s86, v254, 54
	s_waitcnt lgkmcnt(0)
	v_add_f32_e32 v58, v58, v59
	ds_bpermute_b32 v59, v141, v58
	v_readlane_b32 s87, v254, 55
	s_waitcnt lgkmcnt(0)
	v_add_f32_e32 v58, v58, v59
	ds_bpermute_b32 v59, v142, v58
	s_waitcnt lgkmcnt(0)
	v_add_f32_e32 v58, v58, v59
	v_fmamk_f32 v58, v58, 0x3c800000, v174
	v_rsq_f32_e32 v58, v58
	s_nop 0
	v_pk_mul_f32 v[70:71], v[58:59], v[70:71] op_sel_hi:[0,1]
	v_pk_mul_f32 v[56:57], v[58:59], v[56:57] op_sel_hi:[0,1]
	v_pk_mul_f32 v[136:137], v[58:59], v[136:137] op_sel_hi:[0,1]
	v_pk_mul_f32 v[58:59], v[58:59], v[68:69] op_sel_hi:[0,1]
	s_waitcnt lgkmcnt(0)
	v_pk_mul_f32 v[60:61], v[60:61], v[70:71]
	v_pk_mul_f32 v[62:63], v[62:63], v[56:57]
	s_nop 0
	v_pk_mul_f32 v[56:57], v[64:65], v[136:137]
	v_pk_mul_f32 v[58:59], v[58:59], v[66:67] op_sel:[1,0] op_sel_hi:[0,1]
	ds_bpermute_b32 v66, v141, v60
	ds_bpermute_b32 v67, v141, v61
	ds_bpermute_b32 v70, v141, v62
	ds_bpermute_b32 v71, v141, v63
	ds_bpermute_b32 v64, v141, v56
	ds_bpermute_b32 v65, v141, v57
	ds_bpermute_b32 v68, v141, v58
	ds_bpermute_b32 v69, v141, v59
	s_and_saveexec_b64 s[56:57], s[54:55]
	s_cbranch_execz .LBB0_595
	v_readlane_b32 s80, v254, 48
	v_lshl_or_b32 v154, v138, 6, v75
	v_mov_b32_e32 v155, v2
	v_readlane_b32 s84, v254, 52
	v_readlane_b32 s85, v254, 53
	s_mov_b64 s[2:3], 0x1000
	v_readlane_b32 s81, v254, 49
	v_lshl_add_u64 v[146:147], s[84:85], 0, v[154:155]
	v_add_co_u32_e32 v136, vcc, 0x1000, v146
	v_readlane_b32 s82, v254, 50
	s_nop 0
	v_addc_co_u32_e32 v137, vcc, 0, v147, vcc
	global_load_dwordx4 v[136:139], v[136:137], off
	v_lshl_add_u64 v[146:147], v[146:147], 0, s[2:3]
	global_load_dwordx4 v[146:149], v[146:147], off offset:16
	s_nop 0
	global_load_dwordx4 v[150:153], v154, s[84:85]
	s_nop 0
	global_load_dwordx4 v[154:157], v154, s[84:85] offset:16
	v_readlane_b32 s83, v254, 51
	v_readlane_b32 s86, v254, 54
	v_readlane_b32 s87, v254, 55
	s_waitcnt vmcnt(2) lgkmcnt(2)
	v_pk_mul_f32 v[64:65], v[146:147], v[64:65]
	v_pk_mul_f32 v[66:67], v[136:137], v[66:67]
	v_pk_mul_f32 v[70:71], v[138:139], v[70:71]
	s_waitcnt lgkmcnt(0)
	v_pk_mul_f32 v[68:69], v[148:149], v[68:69]
	v_cndmask_b32_e64 v71, v71, -v71, s[48:49]
	v_cndmask_b32_e64 v70, v70, -v70, s[48:49]
	v_cndmask_b32_e64 v67, v67, -v67, s[48:49]
	v_cndmask_b32_e64 v66, v66, -v66, s[48:49]
	v_cndmask_b32_e64 v69, v69, -v69, s[48:49]
	v_cndmask_b32_e64 v68, v68, -v68, s[48:49]
	v_cndmask_b32_e64 v65, v65, -v65, s[48:49]
	v_cndmask_b32_e64 v64, v64, -v64, s[48:49]
	s_waitcnt vmcnt(1)
	v_pk_fma_f32 v[62:63], v[62:63], v[152:153], v[70:71]
	s_waitcnt vmcnt(0)
	v_pk_fma_f32 v[58:59], v[58:59], v[156:157], v[68:69]
	v_pk_fma_f32 v[60:61], v[60:61], v[150:151], v[66:67]
	v_pk_fma_f32 v[56:57], v[56:57], v[154:155], v[64:65]

.LBB0_600:
	s_or_b64 exec, exec, s[56:57]
	v_lshlrev_b32_e32 v52, 16, v48
	v_and_b32_e32 v53, 0xffff0000, v48
	v_pk_mul_f32 v[56:57], v[52:53], v[52:53]
	v_lshlrev_b32_e32 v48, 16, v49
	v_and_b32_e32 v49, 0xffff0000, v49
	v_pk_mul_f32 v[58:59], v[48:49], v[48:49]
	v_add_f32_e32 v56, v56, v57
	v_lshlrev_b32_e32 v54, 16, v50
	v_and_b32_e32 v55, 0xffff0000, v50
	v_add_f32_e32 v56, v58, v56
	v_pk_mul_f32 v[60:61], v[54:55], v[54:55]
	v_add_f32_e32 v56, v59, v56
	v_lshlrev_b32_e32 v50, 16, v51
	v_and_b32_e32 v51, 0xffff0000, v51
	v_add_f32_e32 v56, v60, v56
	v_pk_mul_f32 v[62:63], v[50:51], v[50:51]
	v_add_f32_e32 v56, v61, v56
	v_add_f32_e32 v56, v62, v56
	v_cmp_lt_i32_e32 vcc, v180, v182
	v_add_f32_e32 v56, v63, v56
	v_cndmask_b32_e64 v56, 0, v56, s[42:43]
	v_cndmask_b32_e32 v57, v179, v180, vcc
	v_lshlrev_b32_e32 v58, 2, v57
	ds_bpermute_b32 v57, v58, v56
	v_cmp_lt_i32_e32 vcc, v183, v182
	s_waitcnt lgkmcnt(0)
	v_add_f32_e32 v56, v56, v57
	v_cndmask_b32_e32 v57, v179, v183, vcc
	v_lshlrev_b32_e32 v59, 2, v57
	ds_bpermute_b32 v57, v59, v56
	v_cmp_lt_i32_e32 vcc, v184, v182
	s_waitcnt lgkmcnt(0)
	v_add_f32_e32 v56, v56, v57
	v_cndmask_b32_e32 v57, v179, v184, vcc
	v_lshlrev_b32_e32 v60, 2, v57
	ds_bpermute_b32 v57, v60, v56
	s_waitcnt lgkmcnt(0)
	v_add_f32_e32 v56, v56, v57
	ds_bpermute_b32 v57, v140, v56
	s_waitcnt lgkmcnt(0)
	v_add_f32_e32 v56, v56, v57
	ds_bpermute_b32 v57, v141, v56
	s_waitcnt lgkmcnt(0)
	v_add_f32_e32 v56, v56, v57
	ds_bpermute_b32 v57, v142, v56
	s_and_saveexec_b64 s[56:57], s[42:43]
	s_cbranch_execz .LBB0_602
	ds_read_b128 v[62:65], v162 offset:18944
	ds_read_b128 v[66:69], v162 offset:18960
	s_waitcnt lgkmcnt(0)
	v_add_f32_e32 v56, v56, v57
	v_fmamk_f32 v56, v56, 0x3b2aaaab, v174
	v_rsq_f32_e32 v56, v56
	v_readlane_b32 s80, v254, 48
	v_readlane_b32 s84, v254, 52
	v_readlane_b32 s85, v254, 53
	v_pk_mul_f32 v[52:53], v[56:57], v[52:53] op_sel_hi:[0,1]
	v_pk_mul_f32 v[48:49], v[56:57], v[48:49] op_sel_hi:[0,1]
	v_pk_mul_f32 v[54:55], v[56:57], v[54:55] op_sel_hi:[0,1]
	v_pk_mul_f32 v[50:51], v[56:57], v[50:51] op_sel_hi:[0,1]
	v_readlane_b32 s81, v254, 49
	v_readlane_b32 s82, v254, 50
	v_readlane_b32 s83, v254, 51
	v_readlane_b32 s86, v254, 54
	v_readlane_b32 s87, v254, 55
	s_waitcnt lgkmcnt(0)
	v_pk_mul_f32 v[52:53], v[52:53], v[62:63]
	v_pk_mul_f32 v[56:57], v[48:49], v[64:65]
	s_nop 0
	v_pk_mul_f32 v[54:55], v[54:55], v[66:67]
	v_pk_mul_f32 v[62:63], v[50:51], v[68:69]
	v_cvt_pk_bf16_f32 v48, v52, v53
	v_cvt_pk_bf16_f32 v49, v56, v57
	v_cvt_pk_bf16_f32 v50, v54, v55
	v_cvt_pk_bf16_f32 v51, v62, v63
	v_lshl_add_u64 v[52:53], s[84:85], 0, v[120:121]
	global_store_dwordx4 v[52:53], v[48:51], off
.LBB0_602:
	s_or_b64 exec, exec, s[56:57]
	s_nop 0
	v_lshlrev_b32_e32 v48, 16, v44
	v_and_b32_e32 v49, 0xffff0000, v44
	v_lshlrev_b32_e32 v54, 16, v47
	v_and_b32_e32 v55, 0xffff0000, v47
	v_lshlrev_b32_e32 v56, 16, v46
	s_waitcnt lgkmcnt(0)
	v_and_b32_e32 v57, 0xffff0000, v46
	v_lshlrev_b32_e32 v46, 16, v45
	v_and_b32_e32 v47, 0xffff0000, v45
	v_pk_mul_f32 v[44:45], v[48:49], v[48:49]
	v_pk_mul_f32 v[62:63], v[46:47], v[46:47]
	v_add_f32_e32 v44, v44, v45
	v_add_f32_e32 v44, v62, v44
	v_pk_mul_f32 v[52:53], v[56:57], v[56:57]
	v_add_f32_e32 v44, v63, v44
	v_add_f32_e32 v44, v52, v44
	v_pk_mul_f32 v[50:51], v[54:55], v[54:55]
	v_add_f32_e32 v44, v53, v44
	v_add_f32_e32 v44, v50, v44
	v_add_f32_e32 v44, v51, v44
	v_cndmask_b32_e64 v44, 0, v44, s[38:39]
	ds_bpermute_b32 v45, v58, v44
	v_mul_i32_i24_e32 v50, 0xa00, v147
	s_movk_i32 s2, 0x1200
	v_add3_u32 v50, v143, v50, s2
	v_ashrrev_i32_e32 v51, 31, v50
	s_waitcnt lgkmcnt(0)
	v_add_f32_e32 v44, v44, v45
	ds_bpermute_b32 v45, v59, v44
	v_cndmask_b32_e64 v53, v1, v51, s[54:55]
	v_cndmask_b32_e64 v52, v0, v50, s[54:55]
	s_waitcnt lgkmcnt(0)
	v_add_f32_e32 v44, v44, v45
	ds_bpermute_b32 v45, v60, v44
	s_waitcnt lgkmcnt(0)
	v_add_f32_e32 v44, v44, v45
	ds_bpermute_b32 v45, v140, v44
	s_waitcnt lgkmcnt(0)
	v_add_f32_e32 v44, v44, v45
	ds_bpermute_b32 v45, v141, v44
	s_waitcnt lgkmcnt(0)
	v_add_f32_e32 v44, v44, v45
	ds_bpermute_b32 v45, v142, v44
	s_and_saveexec_b64 s[54:55], s[38:39]
	s_cbranch_execz .LBB0_605
	ds_read_b128 v[58:61], v189 offset:20496
	ds_read_b128 v[62:65], v189 offset:20480
	s_waitcnt lgkmcnt(0)
	v_add_f32_e32 v44, v44, v45
	v_fmamk_f32 v44, v44, 0x3b800000, v174
	v_rsq_f32_e32 v66, v44
	s_nop 0
	v_pk_mul_f32 v[44:45], v[66:67], v[48:49] op_sel_hi:[0,1]
	s_waitcnt lgkmcnt(0)
	v_pk_mul_f32 v[48:49], v[62:63], v[44:45]
	v_pk_mul_f32 v[44:45], v[66:67], v[46:47] op_sel_hi:[0,1]
	v_pk_mul_f32 v[50:51], v[64:65], v[44:45]
	v_pk_mul_f32 v[44:45], v[66:67], v[56:57] op_sel_hi:[0,1]
	v_pk_mul_f32 v[46:47], v[66:67], v[54:55] op_sel_hi:[0,1]
	v_pk_mul_f32 v[44:45], v[58:59], v[44:45]
	v_pk_mul_f32 v[46:47], v[46:47], v[60:61]
	v_lshlrev_b64 v[58:59], 9, v[52:53]
	v_cvt_pk_bf16_f32 v54, v48, v49
	v_cvt_pk_bf16_f32 v55, v50, v51
	v_cvt_pk_bf16_f32 v56, v44, v45
	v_cvt_pk_bf16_f32 v57, v46, v47
	v_lshl_add_u64 v[58:59], v[88:89], 0, v[58:59]
	global_store_dwordx4 v[58:59], v[54:57], off
	s_and_b64 exec, exec, s[52:53]
	s_cbranch_execz .LBB0_605
	v_readlane_b32 s2, v254, 61
	v_readlane_b32 s3, v254, 62
	v_lshlrev_b32_e32 v56, 10, v143
	v_lshl_add_u32 v54, v146, 1, s2
	v_ashrrev_i32_e32 v55, 31, v54
	v_readlane_b32 s2, v253, 28
	v_lshlrev_b64 v[54:55], 18, v[54:55]
	v_readlane_b32 s3, v253, 29
	v_mov_b32_e32 v57, v2
	s_nop 0
	v_lshl_add_u64 v[54:55], s[2:3], 0, v[54:55]
	v_lshl_add_u64 v[54:55], v[54:55], 0, v[56:57]
	v_lshlrev_b32_e32 v56, 2, v72
	v_lshl_add_u64 v[54:55], v[54:55], 0, v[56:57]
	global_store_dwordx4 v[54:55], v[48:51], off
	global_store_dwordx4 v[54:55], v[44:47], off offset:16
